# v46 + attention main loop leads each step with two QK MFMAs, LDS-DMA issue moved behind them (strategy: MFMA-first segment head, asm guide 6.4)
# baseline (speedup 1.0000x reference)
.LBB0_1163:
	s_mov_b32 s24, s39
	s_mov_b32 s25, s38
	v_add_u32_e32 v156, s33, v3
	ds_read_b64_tr_b16 v[152:153], v156 offset:32768
	ds_read_b64_tr_b16 v[154:155], v156 offset:33280
	v_add_f32_e32 v118, v98, v99
	v_add_f32_e32 v118, v100, v118
	v_add_f32_e32 v118, v101, v118
	v_add_f32_e32 v118, v102, v118
	v_add_f32_e32 v118, v103, v118
	v_cvt_pk_bf16_f32 v178, v98, v99
	v_cvt_pk_bf16_f32 v179, v100, v101
	s_waitcnt lgkmcnt(9)
	v_mfma_f32_32x32x16_bf16 v[130:145], v[114:117], v[182:185], v[66:81]
	ds_read_b64_tr_b16 v[98:99], v156 offset:36864
	ds_read_b64_tr_b16 v[100:101], v156 offset:37376
	v_add_f32_e32 v114, v104, v118
	v_add_f32_e32 v114, v105, v114
	v_add_f32_e32 v114, v106, v114
	v_add_f32_e32 v157, v107, v114
	s_waitcnt lgkmcnt(10)
	v_mfma_f32_32x32x16_bf16 v[114:129], v[210:213], v[182:185], v[66:81]
	v_cvt_pk_bf16_f32 v180, v102, v103
	v_cvt_pk_bf16_f32 v181, v104, v105
	v_lshl_add_u64 v[226:227], v[146:147], 0, s[10:11]
	s_add_i32 s27, s33, s35
	s_mov_b32 m0, s27
	s_nop 0
	global_load_lds_dwordx4 v[226:227], off
	v_lshl_add_u64 v[226:227], v[148:149], 0, s[6:7]
	s_add_i32 s27, s39, s34
	s_mov_b32 m0, s27
	s_nop 0
	global_load_lds_dwordx4 v[226:227], off
	ds_read_b64_tr_b16 v[102:103], v156 offset:33792
	ds_read_b64_tr_b16 v[104:105], v156 offset:34304
	v_add_f32_e32 v157, v108, v157
	v_add_f32_e32 v157, v109, v157
	v_add_f32_e32 v157, v110, v157
	v_add_f32_e32 v157, v111, v157
	v_cvt_pk_bf16_f32 v170, v106, v107
	v_cvt_pk_bf16_f32 v171, v108, v109
	s_waitcnt lgkmcnt(11)
	v_mfma_f32_32x32x16_bf16 v[130:145], v[206:209], v[174:177], v[130:145]
	ds_read_b64_tr_b16 v[106:107], v156 offset:37888
	ds_read_b64_tr_b16 v[108:109], v156 offset:38400
	s_waitcnt lgkmcnt(12)
	v_mfma_f32_32x32x16_bf16 v[114:129], v[202:205], v[174:177], v[114:129]
	v_add_f32_e32 v157, v112, v157
	v_add_f32_e32 v157, v113, v157
	v_add_f32_e32 v157, v82, v157
	v_add_f32_e32 v157, v83, v157
	v_cvt_pk_bf16_f32 v172, v110, v111
	v_cvt_pk_bf16_f32 v173, v112, v113
	ds_read_b64_tr_b16 v[110:111], v156 offset:34816
	ds_read_b64_tr_b16 v[112:113], v156 offset:35328
	v_add_f32_e32 v157, v84, v157
	v_add_f32_e32 v157, v85, v157
	v_add_f32_e32 v157, v86, v157
	v_add_f32_e32 v157, v87, v157
	v_cvt_pk_bf16_f32 v166, v82, v83
	v_cvt_pk_bf16_f32 v167, v84, v85
	s_waitcnt lgkmcnt(13)
	v_mfma_f32_32x32x16_bf16 v[130:145], v[198:201], v[12:15], v[130:145]
	ds_read_b64_tr_b16 v[82:83], v156 offset:38912
	ds_read_b64_tr_b16 v[84:85], v156 offset:39424
	s_waitcnt lgkmcnt(14)
	v_mfma_f32_32x32x16_bf16 v[114:129], v[194:197], v[12:15], v[114:129]
	v_add_f32_e32 v157, v88, v157
	v_add_f32_e32 v157, v89, v157
	v_add_f32_e32 v157, v90, v157
	v_add_f32_e32 v157, v91, v157
	v_cvt_pk_bf16_f32 v168, v86, v87
	v_cvt_pk_bf16_f32 v169, v88, v89
	ds_read_b64_tr_b16 v[86:87], v156 offset:35840
	ds_read_b64_tr_b16 v[88:89], v156 offset:36352
	v_add_f32_e32 v157, v92, v157
	v_add_f32_e32 v157, v93, v157
	v_add_f32_e32 v157, v94, v157
	v_add_f32_e32 v157, v95, v157
	v_cvt_pk_bf16_f32 v162, v90, v91
	v_cvt_pk_bf16_f32 v163, v92, v93
	s_waitcnt lgkmcnt(14)
	v_mfma_f32_32x32x16_bf16 v[130:145], v[190:193], v[8:11], v[130:145]
	ds_read_b64_tr_b16 v[90:91], v156 offset:39936
	ds_read_b64_tr_b16 v[92:93], v156 offset:40448
	v_mfma_f32_32x32x16_bf16 v[114:129], v[186:189], v[8:11], v[114:129]
	v_add_f32_e32 v156, v96, v157
	v_add_f32_e32 v156, v97, v156
	v_cvt_pk_bf16_f32 v164, v94, v95
	v_cvt_pk_bf16_f32 v165, v96, v97
	v_add_f32_e32 v160, v219, v156
	s_waitcnt lgkmcnt(14)
	v_mfma_f32_32x32x16_bf16 v[34:49], v[178:181], v[152:155], v[34:49]
	v_exp_f32_e32 v130, v130
	v_exp_f32_e32 v131, v131
	v_exp_f32_e32 v132, v132
	v_exp_f32_e32 v133, v133
	s_waitcnt lgkmcnt(12)
	v_mfma_f32_32x32x16_bf16 v[50:65], v[178:181], v[98:101], v[50:65]
	v_exp_f32_e32 v134, v134
	v_exp_f32_e32 v135, v135
	v_exp_f32_e32 v136, v136
	v_exp_f32_e32 v137, v137
	v_add_u32_e32 v98, s24, v7
	ds_read_b128 v[94:97], v98
	ds_read_b128 v[152:155], v98 offset:512
	s_waitcnt lgkmcnt(12)
	v_mfma_f32_32x32x16_bf16 v[34:49], v[170:173], v[102:105], v[34:49]
	v_exp_f32_e32 v138, v138
	v_exp_f32_e32 v139, v139
	v_exp_f32_e32 v140, v140
	v_exp_f32_e32 v141, v141
	ds_read_b128 v[156:159], v98 offset:2048
	ds_read_b128 v[186:189], v98 offset:2560
	s_waitcnt lgkmcnt(12)
	v_mfma_f32_32x32x16_bf16 v[50:65], v[170:173], v[106:109], v[50:65]
	v_exp_f32_e32 v142, v142
	v_exp_f32_e32 v143, v143
	v_exp_f32_e32 v144, v144
	v_exp_f32_e32 v145, v145
	ds_read_b128 v[190:193], v98 offset:4096
	ds_read_b128 v[194:197], v98 offset:4608
	s_waitcnt lgkmcnt(12)
	v_mfma_f32_32x32x16_bf16 v[34:49], v[166:169], v[110:113], v[34:49]
	v_exp_f32_e32 v114, v114
	v_exp_f32_e32 v115, v115
	v_exp_f32_e32 v116, v116
	v_exp_f32_e32 v117, v117
	ds_read_b128 v[198:201], v98 offset:6144
	ds_read_b128 v[202:205], v98 offset:6656
	s_waitcnt lgkmcnt(12)
	v_mfma_f32_32x32x16_bf16 v[50:65], v[166:169], v[82:85], v[50:65]
	v_exp_f32_e32 v118, v118
	v_exp_f32_e32 v119, v119
	v_exp_f32_e32 v120, v120
	v_exp_f32_e32 v121, v121
	s_waitcnt lgkmcnt(10)
	v_mfma_f32_32x32x16_bf16 v[34:49], v[162:165], v[86:89], v[34:49]
	v_exp_f32_e32 v122, v122
	v_exp_f32_e32 v123, v123
	v_exp_f32_e32 v124, v124
	v_exp_f32_e32 v125, v125
	s_waitcnt lgkmcnt(8)
	v_mfma_f32_32x32x16_bf16 v[50:65], v[162:165], v[90:93], v[50:65]
	v_exp_f32_e32 v126, v126
	v_exp_f32_e32 v127, v127
	v_exp_f32_e32 v128, v128
	v_exp_f32_e32 v129, v129
	s_add_i32 s27, s39, 0x2000
	s_cmpk_lg_i32 s39, 0x6000
	s_cselect_b32 s38, s27, 0
	v_add_u32_e32 v161, s25, v3
	ds_read_b64_tr_b16 v[206:207], v161 offset:32768
	ds_read_b64_tr_b16 v[208:209], v161 offset:33280
	s_waitcnt lgkmcnt(9)
	v_mfma_f32_32x32x16_bf16 v[98:113], v[94:97], v[182:185], v[66:81]
	v_add_f32_e32 v82, v130, v131
	v_add_f32_e32 v82, v132, v82
	v_add_f32_e32 v82, v133, v82
	v_add_f32_e32 v82, v134, v82
	v_add_f32_e32 v82, v135, v82
	v_cvt_pk_bf16_f32 v178, v130, v131
	v_cvt_pk_bf16_f32 v179, v132, v133
	ds_read_b64_tr_b16 v[130:131], v161 offset:36864
	ds_read_b64_tr_b16 v[132:133], v161 offset:37376
	v_add_f32_e32 v82, v136, v82
	v_add_f32_e32 v82, v137, v82
	v_add_f32_e32 v82, v138, v82
	v_add_f32_e32 v162, v139, v82
	s_waitcnt lgkmcnt(10)
	v_mfma_f32_32x32x16_bf16 v[82:97], v[152:155], v[182:185], v[66:81]
	v_cvt_pk_bf16_f32 v180, v134, v135
	v_cvt_pk_bf16_f32 v181, v136, v137
	v_lshl_add_u64 v[226:227], v[146:147], 0, s[12:13]
	s_add_i32 s27, s25, s35
	s_mov_b32 m0, s27
	s_nop 0
	global_load_lds_dwordx4 v[226:227], off
	v_lshl_add_u64 v[148:149], v[148:149], 0, s[8:9]
	s_add_i32 s27, s38, s34
	s_mov_b32 m0, s27
	s_nop 0
	global_load_lds_dwordx4 v[148:149], off
	ds_read_b64_tr_b16 v[134:135], v161 offset:33792
	ds_read_b64_tr_b16 v[136:137], v161 offset:34304
	s_waitcnt lgkmcnt(11)
	v_mfma_f32_32x32x16_bf16 v[98:113], v[156:159], v[174:177], v[98:113]
	v_add_f32_e32 v152, v140, v162
	v_add_f32_e32 v152, v141, v152
	v_add_f32_e32 v152, v142, v152
	v_add_f32_e32 v152, v143, v152
	v_cvt_pk_bf16_f32 v170, v138, v139
	v_cvt_pk_bf16_f32 v171, v140, v141
	ds_read_b64_tr_b16 v[138:139], v161 offset:37888
	ds_read_b64_tr_b16 v[140:141], v161 offset:38400
	s_waitcnt lgkmcnt(12)
	v_mfma_f32_32x32x16_bf16 v[82:97], v[186:189], v[174:177], v[82:97]
	v_add_f32_e32 v152, v144, v152
	v_add_f32_e32 v152, v145, v152
	v_add_f32_e32 v152, v114, v152
	v_add_f32_e32 v152, v115, v152
	v_cvt_pk_bf16_f32 v172, v142, v143
	v_cvt_pk_bf16_f32 v173, v144, v145
	ds_read_b64_tr_b16 v[142:143], v161 offset:34816
	ds_read_b64_tr_b16 v[144:145], v161 offset:35328
	s_waitcnt lgkmcnt(13)
	v_mfma_f32_32x32x16_bf16 v[98:113], v[190:193], v[12:15], v[98:113]
	v_add_f32_e32 v152, v116, v152
	v_add_f32_e32 v152, v117, v152
	v_add_f32_e32 v152, v118, v152
	v_add_f32_e32 v156, v119, v152
	v_cvt_pk_bf16_f32 v166, v114, v115
	v_cvt_pk_bf16_f32 v167, v116, v117
	ds_read_b64_tr_b16 v[152:153], v161 offset:38912
	ds_read_b64_tr_b16 v[154:155], v161 offset:39424
	s_waitcnt lgkmcnt(14)
	v_mfma_f32_32x32x16_bf16 v[82:97], v[194:197], v[12:15], v[82:97]
	v_add_f32_e32 v114, v120, v156
	v_add_f32_e32 v114, v121, v114
	v_add_f32_e32 v114, v122, v114
	v_add_f32_e32 v114, v123, v114
	v_cvt_pk_bf16_f32 v168, v118, v119
	v_cvt_pk_bf16_f32 v169, v120, v121
	ds_read_b64_tr_b16 v[118:119], v161 offset:35840
	ds_read_b64_tr_b16 v[120:121], v161 offset:36352
	s_waitcnt lgkmcnt(14)
	v_mfma_f32_32x32x16_bf16 v[98:113], v[198:201], v[8:11], v[98:113]
	v_add_f32_e32 v114, v124, v114
	v_add_f32_e32 v114, v125, v114
	v_add_f32_e32 v114, v126, v114
	v_add_f32_e32 v114, v127, v114
	v_cvt_pk_bf16_f32 v162, v122, v123
	v_cvt_pk_bf16_f32 v163, v124, v125
	ds_read_b64_tr_b16 v[122:123], v161 offset:39936
	ds_read_b64_tr_b16 v[124:125], v161 offset:40448
	v_mfma_f32_32x32x16_bf16 v[82:97], v[202:205], v[8:11], v[82:97]
	v_add_f32_e32 v114, v128, v114
	v_add_f32_e32 v114, v129, v114
	v_cvt_pk_bf16_f32 v164, v126, v127
	v_cvt_pk_bf16_f32 v165, v128, v129
	v_add_f32_e32 v219, v160, v114
	s_waitcnt lgkmcnt(14)
	v_mfma_f32_32x32x16_bf16 v[34:49], v[178:181], v[206:209], v[34:49]
	v_exp_f32_e32 v98, v98
	v_exp_f32_e32 v99, v99
	v_exp_f32_e32 v100, v100
	v_exp_f32_e32 v101, v101
	s_waitcnt lgkmcnt(12)
	v_mfma_f32_32x32x16_bf16 v[50:65], v[178:181], v[130:133], v[50:65]
	v_exp_f32_e32 v102, v102
	v_exp_f32_e32 v103, v103
	v_exp_f32_e32 v104, v104
	v_exp_f32_e32 v105, v105
	v_add_u32_e32 v126, s38, v7
	ds_read_b128 v[114:117], v126
	ds_read_b128 v[210:213], v126 offset:512
	s_waitcnt lgkmcnt(12)
	v_mfma_f32_32x32x16_bf16 v[34:49], v[170:173], v[134:137], v[34:49]
	v_exp_f32_e32 v106, v106
	v_exp_f32_e32 v107, v107
	v_exp_f32_e32 v108, v108
	v_exp_f32_e32 v109, v109
	ds_read_b128 v[206:209], v126 offset:2048
	ds_read_b128 v[202:205], v126 offset:2560
	s_waitcnt lgkmcnt(12)
	v_mfma_f32_32x32x16_bf16 v[50:65], v[170:173], v[138:141], v[50:65]
	v_exp_f32_e32 v110, v110
	v_exp_f32_e32 v111, v111
	v_exp_f32_e32 v112, v112
	v_exp_f32_e32 v113, v113
	ds_read_b128 v[198:201], v126 offset:4096
	ds_read_b128 v[194:197], v126 offset:4608
	s_waitcnt lgkmcnt(12)
	v_mfma_f32_32x32x16_bf16 v[34:49], v[166:169], v[142:145], v[34:49]
	v_exp_f32_e32 v82, v82
	v_exp_f32_e32 v83, v83
	v_exp_f32_e32 v84, v84
	v_exp_f32_e32 v85, v85
	ds_read_b128 v[190:193], v126 offset:6144
	ds_read_b128 v[186:189], v126 offset:6656
	s_waitcnt lgkmcnt(12)
	v_mfma_f32_32x32x16_bf16 v[50:65], v[166:169], v[152:155], v[50:65]
	v_exp_f32_e32 v86, v86
	v_exp_f32_e32 v87, v87
	v_exp_f32_e32 v88, v88
	v_exp_f32_e32 v89, v89
	s_waitcnt lgkmcnt(10)
	v_mfma_f32_32x32x16_bf16 v[34:49], v[162:165], v[118:121], v[34:49]
	v_exp_f32_e32 v90, v90
	v_exp_f32_e32 v91, v91
	v_exp_f32_e32 v92, v92
	v_exp_f32_e32 v93, v93
	s_waitcnt lgkmcnt(8)
	v_mfma_f32_32x32x16_bf16 v[50:65], v[162:165], v[122:125], v[50:65]
	v_exp_f32_e32 v94, v94
	v_exp_f32_e32 v95, v95
	v_exp_f32_e32 v96, v96
	v_exp_f32_e32 v97, v97
	s_add_i32 s25, s38, 0x2000
	s_waitcnt vmcnt(0) lgkmcnt(0)
	s_barrier
	s_cmpk_lg_i32 s38, 0x6000
	s_cselect_b32 s39, s25, 0
	s_add_i32 s37, s37, 2
	v_lshl_add_u64 v[146:147], v[146:147], 0, s[8:9]
	s_cmpk_gt_u32 s37, 0xf9
	s_mov_b32 s33, s24
	s_cbranch_scc0 .LBB0_1163
	s_and_b32 s25, s36, 0x3fffffc0
	s_cmp_lg_u32 0, -1
	s_cselect_b32 s27, 0, 0
	s_add_i32 s27, s27, 0x8000
	s_lshl_b32 s25, s25, 2
	v_add3_u32 v218, v151, s27, v150
	s_add_i32 s27, s25, 0
	s_add_i32 s27, s27, 0x10000
	v_lshl_add_u64 v[16:17], v[16:17], 0, s[14:15]
	s_add_i32 s25, s24, s35
	s_mov_b32 s28, m0
	s_mov_b32 m0, s25
	s_nop 0
	global_load_lds_dwordx4 v[16:17], off
	s_mov_b32 m0, s28
	v_lshl_add_u64 v[16:17], v[4:5], 0, s[16:17]
	s_add_i32 s25, s39, s34
	s_mov_b32 s28, m0
	s_mov_b32 m0, s25
	s_nop 0
	global_load_lds_dwordx4 v[16:17], off
	s_mov_b32 m0, s28
	v_add_u32_e32 v16, s24, v3
	ds_read_b64_tr_b16 v[130:131], v16 offset:32768
	ds_read_b64_tr_b16 v[132:133], v16 offset:33280
	v_add_f32_e32 v17, v98, v99
	v_add_f32_e32 v17, v100, v17
	v_add_f32_e32 v17, v101, v17
	v_add_f32_e32 v17, v102, v17
	v_add_f32_e32 v17, v103, v17
	v_cvt_pk_bf16_f32 v178, v98, v99
	v_cvt_pk_bf16_f32 v179, v100, v101
	s_waitcnt lgkmcnt(9)
	v_mfma_f32_32x32x16_bf16 v[146:161], v[114:117], v[182:185], v[66:81]
	ds_read_b64_tr_b16 v[98:99], v16 offset:36864
	ds_read_b64_tr_b16 v[100:101], v16 offset:37376
	v_add_f32_e32 v17, v104, v17
	v_add_f32_e32 v17, v105, v17
	v_add_f32_e32 v17, v106, v17
	v_add_f32_e32 v17, v107, v17
	v_cvt_pk_bf16_f32 v180, v102, v103
	v_cvt_pk_bf16_f32 v181, v104, v105
	s_waitcnt lgkmcnt(10)
	v_mfma_f32_32x32x16_bf16 v[114:129], v[210:213], v[182:185], v[66:81]
	ds_read_b64_tr_b16 v[102:103], v16 offset:33792
	ds_read_b64_tr_b16 v[104:105], v16 offset:34304
	v_add_f32_e32 v17, v108, v17
	v_add_f32_e32 v17, v109, v17
	v_add_f32_e32 v17, v110, v17
	v_add_f32_e32 v17, v111, v17
	v_cvt_pk_bf16_f32 v170, v106, v107
	v_cvt_pk_bf16_f32 v171, v108, v109
	s_waitcnt lgkmcnt(11)
	v_mfma_f32_32x32x16_bf16 v[146:161], v[206:209], v[174:177], v[146:161]
	ds_read_b64_tr_b16 v[106:107], v16 offset:37888
	ds_read_b64_tr_b16 v[108:109], v16 offset:38400
	v_add_f32_e32 v17, v112, v17
	v_add_f32_e32 v17, v113, v17
	v_add_f32_e32 v17, v82, v17
	v_add_f32_e32 v17, v83, v17
	v_cvt_pk_bf16_f32 v172, v110, v111
	v_cvt_pk_bf16_f32 v173, v112, v113
	s_waitcnt lgkmcnt(12)
	v_mfma_f32_32x32x16_bf16 v[114:129], v[202:205], v[174:177], v[114:129]
	ds_read_b64_tr_b16 v[110:111], v16 offset:34816
	ds_read_b64_tr_b16 v[112:113], v16 offset:35328
	v_add_f32_e32 v17, v84, v17
	v_add_f32_e32 v17, v85, v17
	v_add_f32_e32 v17, v86, v17
	v_add_f32_e32 v17, v87, v17
	v_cvt_pk_bf16_f32 v166, v82, v83
	v_cvt_pk_bf16_f32 v167, v84, v85
	s_waitcnt lgkmcnt(13)
	v_mfma_f32_32x32x16_bf16 v[146:161], v[198:201], v[12:15], v[146:161]
	ds_read_b64_tr_b16 v[82:83], v16 offset:38912
	ds_read_b64_tr_b16 v[84:85], v16 offset:39424
	v_add_f32_e32 v17, v88, v17
	v_add_f32_e32 v17, v89, v17
	v_add_f32_e32 v17, v90, v17
	v_add_f32_e32 v17, v91, v17
	v_cvt_pk_bf16_f32 v168, v86, v87
	v_cvt_pk_bf16_f32 v169, v88, v89
	s_waitcnt lgkmcnt(14)
	v_mfma_f32_32x32x16_bf16 v[114:129], v[194:197], v[12:15], v[114:129]
	ds_read_b64_tr_b16 v[86:87], v16 offset:35840
	ds_read_b64_tr_b16 v[88:89], v16 offset:36352
	v_add_f32_e32 v17, v92, v17
	v_add_f32_e32 v17, v93, v17
	v_add_f32_e32 v17, v94, v17
	v_add_f32_e32 v17, v95, v17
	v_cvt_pk_bf16_f32 v162, v90, v91
	v_cvt_pk_bf16_f32 v163, v92, v93
	s_waitcnt lgkmcnt(14)
	v_mfma_f32_32x32x16_bf16 v[146:161], v[190:193], v[8:11], v[146:161]
	ds_read_b64_tr_b16 v[90:91], v16 offset:39936
	ds_read_b64_tr_b16 v[92:93], v16 offset:40448
	v_add_f32_e32 v16, v96, v17
	v_add_f32_e32 v16, v97, v16
	v_add_f32_e32 v16, 0, v16
	v_cvt_pk_bf16_f32 v164, v94, v95
	v_cvt_pk_bf16_f32 v165, v96, v97
	v_mfma_f32_32x32x16_bf16 v[114:129], v[186:189], v[8:11], v[114:129]
	v_add_f32_e32 v202, v219, v16
	s_waitcnt lgkmcnt(14)
	v_mfma_f32_32x32x16_bf16 v[34:49], v[178:181], v[130:133], v[34:49]
	s_nop 0
	v_exp_f32_e32 v146, v146
	v_exp_f32_e32 v147, v147
	v_exp_f32_e32 v148, v148
	v_exp_f32_e32 v149, v149
	s_waitcnt lgkmcnt(12)
	v_mfma_f32_32x32x16_bf16 v[50:65], v[178:181], v[98:101], v[50:65]
	v_exp_f32_e32 v150, v150
	v_exp_f32_e32 v151, v151
	v_exp_f32_e32 v152, v152
	v_exp_f32_e32 v153, v153
	v_add_u32_e32 v16, s39, v7
	ds_read_b128 v[94:97], v16
	ds_read_b128 v[98:101], v16 offset:512
	s_waitcnt lgkmcnt(12)
	v_mfma_f32_32x32x16_bf16 v[34:49], v[170:173], v[102:105], v[34:49]
	v_exp_f32_e32 v154, v154
	v_exp_f32_e32 v155, v155
	v_exp_f32_e32 v156, v156
	v_exp_f32_e32 v157, v157
	ds_read_b128 v[102:105], v16 offset:2048
	ds_read_b128 v[186:189], v16 offset:2560
	s_waitcnt lgkmcnt(12)
	v_mfma_f32_32x32x16_bf16 v[50:65], v[170:173], v[106:109], v[50:65]
	v_exp_f32_e32 v158, v158
	v_exp_f32_e32 v159, v159
	v_exp_f32_e32 v160, v160
	v_exp_f32_e32 v161, v161
	ds_read_b128 v[106:109], v16 offset:4096
	ds_read_b128 v[190:193], v16 offset:4608
	s_waitcnt lgkmcnt(12)
	v_mfma_f32_32x32x16_bf16 v[34:49], v[166:169], v[110:113], v[34:49]
	v_exp_f32_e32 v114, v114
	v_exp_f32_e32 v115, v115
	v_exp_f32_e32 v116, v116
	v_exp_f32_e32 v117, v117
	ds_read_b128 v[110:113], v16 offset:6144
	ds_read_b128 v[194:197], v16 offset:6656
	s_waitcnt lgkmcnt(12)
	v_mfma_f32_32x32x16_bf16 v[50:65], v[166:169], v[82:85], v[50:65]
	v_exp_f32_e32 v118, v118
	v_exp_f32_e32 v119, v119
	v_exp_f32_e32 v120, v120
	v_exp_f32_e32 v121, v121
	s_waitcnt lgkmcnt(10)
	v_mfma_f32_32x32x16_bf16 v[34:49], v[162:165], v[86:89], v[34:49]
	v_exp_f32_e32 v122, v122
	v_exp_f32_e32 v123, v123
	v_exp_f32_e32 v124, v124
	v_exp_f32_e32 v125, v125
	s_waitcnt lgkmcnt(8)
	v_mfma_f32_32x32x16_bf16 v[50:65], v[162:165], v[90:93], v[50:65]
	v_exp_f32_e32 v126, v126
	v_exp_f32_e32 v127, v127
	v_exp_f32_e32 v128, v128
	v_exp_f32_e32 v129, v129
	s_add_i32 s24, s39, 0x2000
	s_cmpk_lg_i32 s39, 0x6000
	s_cselect_b32 s25, s24, 0
	v_lshl_add_u64 v[16:17], v[4:5], 0, s[20:21]
	s_add_i32 s24, s25, s34
	s_mov_b32 s28, m0
	s_mov_b32 m0, s24
	s_nop 0
	global_load_lds_dwordx4 v[16:17], off
	s_mov_b32 m0, s28
	v_add_u32_e32 v16, s38, v3
	ds_read_b64_tr_b16 v[198:199], v16 offset:32768
	ds_read_b64_tr_b16 v[200:201], v16 offset:33280
	v_add_f32_e32 v17, v146, v147
	v_add_f32_e32 v17, v148, v17
	v_add_f32_e32 v17, v149, v17
	v_add_f32_e32 v17, v150, v17
	v_add_f32_e32 v17, v151, v17
	v_cvt_pk_bf16_f32 v178, v146, v147
	v_cvt_pk_bf16_f32 v179, v148, v149
	s_waitcnt lgkmcnt(9)
	v_mfma_f32_32x32x16_bf16 v[130:145], v[94:97], v[182:185], v[66:81]
	ds_read_b64_tr_b16 v[146:147], v16 offset:36864
	ds_read_b64_tr_b16 v[148:149], v16 offset:37376
	v_add_f32_e32 v17, v152, v17
	v_add_f32_e32 v17, v153, v17
	v_add_f32_e32 v17, v154, v17
	v_add_f32_e32 v17, v155, v17
	v_cvt_pk_bf16_f32 v180, v150, v151
	v_cvt_pk_bf16_f32 v181, v152, v153
	s_waitcnt lgkmcnt(10)
	v_mfma_f32_32x32x16_bf16 v[82:97], v[98:101], v[182:185], v[66:81]
	ds_read_b64_tr_b16 v[98:99], v16 offset:33792
	ds_read_b64_tr_b16 v[100:101], v16 offset:34304
	v_add_f32_e32 v17, v156, v17
	v_add_f32_e32 v17, v157, v17
	v_add_f32_e32 v17, v158, v17
	v_add_f32_e32 v17, v159, v17
	v_cvt_pk_bf16_f32 v170, v154, v155
	v_cvt_pk_bf16_f32 v171, v156, v157
	s_waitcnt lgkmcnt(11)
	v_mfma_f32_32x32x16_bf16 v[130:145], v[102:105], v[174:177], v[130:145]
	ds_read_b64_tr_b16 v[102:103], v16 offset:37888
	ds_read_b64_tr_b16 v[104:105], v16 offset:38400
	v_add_f32_e32 v17, v160, v17
	v_add_f32_e32 v17, v161, v17
	v_add_f32_e32 v17, v114, v17
	v_add_f32_e32 v17, v115, v17
	v_cvt_pk_bf16_f32 v172, v158, v159
	v_cvt_pk_bf16_f32 v173, v160, v161
	s_waitcnt lgkmcnt(12)
	v_mfma_f32_32x32x16_bf16 v[82:97], v[186:189], v[174:177], v[82:97]
	ds_read_b64_tr_b16 v[150:151], v16 offset:34816
	ds_read_b64_tr_b16 v[152:153], v16 offset:35328
	v_add_f32_e32 v17, v116, v17
	v_add_f32_e32 v17, v117, v17
	v_add_f32_e32 v17, v118, v17
	v_add_f32_e32 v17, v119, v17
	v_cvt_pk_bf16_f32 v166, v114, v115
	v_cvt_pk_bf16_f32 v167, v116, v117
	s_waitcnt lgkmcnt(13)
	v_mfma_f32_32x32x16_bf16 v[130:145], v[106:109], v[12:15], v[130:145]
	ds_read_b64_tr_b16 v[106:107], v16 offset:38912
	ds_read_b64_tr_b16 v[108:109], v16 offset:39424
	v_add_f32_e32 v17, v120, v17
	v_add_f32_e32 v17, v121, v17
	v_add_f32_e32 v17, v122, v17
	v_add_f32_e32 v17, v123, v17
	v_cvt_pk_bf16_f32 v168, v118, v119
	v_cvt_pk_bf16_f32 v169, v120, v121
	s_waitcnt lgkmcnt(14)
	v_mfma_f32_32x32x16_bf16 v[82:97], v[190:193], v[12:15], v[82:97]
	ds_read_b64_tr_b16 v[114:115], v16 offset:35840
	ds_read_b64_tr_b16 v[116:117], v16 offset:36352
	v_add_f32_e32 v17, v124, v17
	v_add_f32_e32 v17, v125, v17
	v_add_f32_e32 v17, v126, v17
	v_add_f32_e32 v17, v127, v17
	v_cvt_pk_bf16_f32 v162, v122, v123
	v_cvt_pk_bf16_f32 v163, v124, v125
	s_waitcnt lgkmcnt(14)
	v_mfma_f32_32x32x16_bf16 v[130:145], v[110:113], v[8:11], v[130:145]
	ds_read_b64_tr_b16 v[110:111], v16 offset:39936
	ds_read_b64_tr_b16 v[112:113], v16 offset:40448
	v_add_f32_e32 v16, v128, v17
	v_add_f32_e32 v16, v129, v16
	v_add_f32_e32 v16, 0, v16
	v_cvt_pk_bf16_f32 v164, v126, v127
	v_cvt_pk_bf16_f32 v165, v128, v129
	v_mfma_f32_32x32x16_bf16 v[82:97], v[194:197], v[8:11], v[82:97]
	v_add_f32_e32 v16, v202, v16
	s_waitcnt lgkmcnt(14)
	v_mfma_f32_32x32x16_bf16 v[34:49], v[178:181], v[198:201], v[34:49]
	s_nop 0
	v_exp_f32_e32 v130, v130
	v_exp_f32_e32 v131, v131
	v_exp_f32_e32 v132, v132
	v_exp_f32_e32 v133, v133
	s_waitcnt lgkmcnt(12)
	v_mfma_f32_32x32x16_bf16 v[50:65], v[178:181], v[146:149], v[50:65]
	v_exp_f32_e32 v134, v134
	v_exp_f32_e32 v135, v135
	v_exp_f32_e32 v136, v136
	v_exp_f32_e32 v137, v137
	v_add_u32_e32 v17, s25, v7
	ds_read_b128 v[146:149], v17
	ds_read_b128 v[154:157], v17 offset:512
	s_waitcnt lgkmcnt(12)
	v_mfma_f32_32x32x16_bf16 v[34:49], v[170:173], v[98:101], v[34:49]
	v_exp_f32_e32 v138, v138
	v_exp_f32_e32 v139, v139
	v_exp_f32_e32 v140, v140
	v_exp_f32_e32 v141, v141
	ds_read_b128 v[158:161], v17 offset:2048
	ds_read_b128 v[186:189], v17 offset:2560
	s_waitcnt lgkmcnt(12)
	v_mfma_f32_32x32x16_bf16 v[50:65], v[170:173], v[102:105], v[50:65]
	v_exp_f32_e32 v142, v142
	v_exp_f32_e32 v143, v143
	v_exp_f32_e32 v144, v144
	v_exp_f32_e32 v145, v145
	ds_read_b128 v[190:193], v17 offset:4096
	ds_read_b128 v[194:197], v17 offset:4608
	s_waitcnt lgkmcnt(12)
	v_mfma_f32_32x32x16_bf16 v[34:49], v[166:169], v[150:153], v[34:49]
	v_exp_f32_e32 v82, v82
	v_exp_f32_e32 v83, v83
	v_exp_f32_e32 v84, v84
	v_exp_f32_e32 v85, v85
	ds_read_b128 v[150:153], v17 offset:6144
	ds_read_b128 v[198:201], v17 offset:6656
	s_waitcnt lgkmcnt(12)
	v_mfma_f32_32x32x16_bf16 v[50:65], v[166:169], v[106:109], v[50:65]
	v_exp_f32_e32 v86, v86
	v_exp_f32_e32 v87, v87
	v_exp_f32_e32 v88, v88
	v_exp_f32_e32 v89, v89
	s_waitcnt lgkmcnt(10)
	v_mfma_f32_32x32x16_bf16 v[34:49], v[162:165], v[114:117], v[34:49]
	v_exp_f32_e32 v90, v90
	v_exp_f32_e32 v91, v91
	v_exp_f32_e32 v92, v92
	v_exp_f32_e32 v93, v93
	s_waitcnt lgkmcnt(8)
	v_mfma_f32_32x32x16_bf16 v[50:65], v[162:165], v[110:113], v[50:65]
	v_exp_f32_e32 v94, v94
	v_exp_f32_e32 v95, v95
	v_exp_f32_e32 v96, v96
	v_exp_f32_e32 v97, v97
	s_waitcnt vmcnt(0) lgkmcnt(0)
	s_barrier
	s_add_i32 s24, s25, 0x2000
	s_cmpk_lg_i32 s25, 0x6000
	s_cselect_b32 s24, s24, 0
	v_lshl_add_u64 v[4:5], v[4:5], 0, s[14:15]
	s_add_i32 s28, s24, s34
	s_mov_b32 s29, m0
	s_mov_b32 m0, s28
	s_nop 0
	global_load_lds_dwordx4 v[4:5], off
	s_mov_b32 m0, s29
	v_add_u32_e32 v4, s39, v3
	ds_read_b64_tr_b16 v[202:203], v4 offset:32768
	ds_read_b64_tr_b16 v[204:205], v4 offset:33280
	v_add_f32_e32 v5, v130, v131
	v_add_f32_e32 v5, v132, v5
	v_add_f32_e32 v5, v133, v5
	v_add_f32_e32 v5, v134, v5
	v_add_f32_e32 v5, v135, v5
	v_cvt_pk_bf16_f32 v178, v130, v131
	v_cvt_pk_bf16_f32 v179, v132, v133
	s_waitcnt lgkmcnt(9)
	v_mfma_f32_32x32x16_bf16 v[114:129], v[146:149], v[182:185], v[66:81]
	ds_read_b64_tr_b16 v[130:131], v4 offset:36864
	ds_read_b64_tr_b16 v[132:133], v4 offset:37376
	v_add_f32_e32 v5, v136, v5
	v_add_f32_e32 v5, v137, v5
	v_add_f32_e32 v5, v138, v5
	v_add_f32_e32 v5, v139, v5
	v_cvt_pk_bf16_f32 v180, v134, v135
	v_cvt_pk_bf16_f32 v181, v136, v137
	s_waitcnt lgkmcnt(10)
	v_mfma_f32_32x32x16_bf16 v[98:113], v[154:157], v[182:185], v[66:81]
	ds_read_b64_tr_b16 v[134:135], v4 offset:33792
	ds_read_b64_tr_b16 v[136:137], v4 offset:34304
	v_add_f32_e32 v5, v140, v5
	v_add_f32_e32 v5, v141, v5
	v_add_f32_e32 v5, v142, v5
	v_add_f32_e32 v5, v143, v5
	v_cvt_pk_bf16_f32 v170, v138, v139
	v_cvt_pk_bf16_f32 v171, v140, v141
	s_waitcnt lgkmcnt(11)
	v_mfma_f32_32x32x16_bf16 v[114:129], v[158:161], v[174:177], v[114:129]
	ds_read_b64_tr_b16 v[138:139], v4 offset:37888
	ds_read_b64_tr_b16 v[140:141], v4 offset:38400
	v_add_f32_e32 v5, v144, v5
	v_add_f32_e32 v5, v145, v5
	v_add_f32_e32 v5, v82, v5
	v_add_f32_e32 v5, v83, v5
	v_cvt_pk_bf16_f32 v172, v142, v143
	v_cvt_pk_bf16_f32 v173, v144, v145
	s_waitcnt lgkmcnt(12)
	v_mfma_f32_32x32x16_bf16 v[98:113], v[186:189], v[174:177], v[98:113]
	ds_read_b64_tr_b16 v[142:143], v4 offset:34816
	ds_read_b64_tr_b16 v[144:145], v4 offset:35328
	v_add_f32_e32 v5, v84, v5
	v_add_f32_e32 v5, v85, v5
	v_add_f32_e32 v5, v86, v5
	v_add_f32_e32 v5, v87, v5
	v_cvt_pk_bf16_f32 v166, v82, v83
	v_cvt_pk_bf16_f32 v167, v84, v85
	s_waitcnt lgkmcnt(13)
	v_mfma_f32_32x32x16_bf16 v[114:129], v[190:193], v[12:15], v[114:129]
	ds_read_b64_tr_b16 v[82:83], v4 offset:38912
	ds_read_b64_tr_b16 v[84:85], v4 offset:39424
	v_add_f32_e32 v5, v88, v5
	v_add_f32_e32 v5, v89, v5
	v_add_f32_e32 v5, v90, v5
	v_add_f32_e32 v5, v91, v5
	v_cvt_pk_bf16_f32 v168, v86, v87
	v_cvt_pk_bf16_f32 v169, v88, v89
	s_waitcnt lgkmcnt(14)
	v_mfma_f32_32x32x16_bf16 v[98:113], v[194:197], v[12:15], v[98:113]
	ds_read_b64_tr_b16 v[86:87], v4 offset:35840
	ds_read_b64_tr_b16 v[88:89], v4 offset:36352
	v_add_f32_e32 v5, v92, v5
	v_add_f32_e32 v5, v93, v5
	v_add_f32_e32 v5, v94, v5
	v_add_f32_e32 v5, v95, v5
	v_cvt_pk_bf16_f32 v162, v90, v91
	v_cvt_pk_bf16_f32 v163, v92, v93
	s_waitcnt lgkmcnt(14)
	v_mfma_f32_32x32x16_bf16 v[114:129], v[150:153], v[8:11], v[114:129]
	ds_read_b64_tr_b16 v[90:91], v4 offset:39936
	ds_read_b64_tr_b16 v[92:93], v4 offset:40448
	v_add_f32_e32 v4, v96, v5
	v_add_f32_e32 v4, v97, v4
	v_add_f32_e32 v4, 0, v4
	v_cvt_pk_bf16_f32 v164, v94, v95
	v_cvt_pk_bf16_f32 v165, v96, v97
	v_mfma_f32_32x32x16_bf16 v[98:113], v[198:201], v[8:11], v[98:113]
	v_add_f32_e32 v4, v16, v4
	s_waitcnt lgkmcnt(14)
	v_mfma_f32_32x32x16_bf16 v[34:49], v[178:181], v[202:205], v[34:49]
	s_nop 0
	v_exp_f32_e32 v114, v114
	v_exp_f32_e32 v115, v115
	v_exp_f32_e32 v116, v116
	v_exp_f32_e32 v117, v117
	s_waitcnt lgkmcnt(12)
	v_mfma_f32_32x32x16_bf16 v[50:65], v[178:181], v[130:133], v[50:65]
	v_exp_f32_e32 v118, v118
	v_exp_f32_e32 v119, v119
	v_exp_f32_e32 v120, v120
	v_exp_f32_e32 v121, v121
	v_add_u32_e32 v5, s24, v7
	ds_read_b128 v[94:97], v5
	s_waitcnt lgkmcnt(11)
	v_mfma_f32_32x32x16_bf16 v[34:49], v[170:173], v[134:137], v[34:49]
	v_exp_f32_e32 v122, v122
	v_exp_f32_e32 v123, v123
	v_exp_f32_e32 v124, v124
	v_exp_f32_e32 v125, v125
	ds_read_b128 v[130:133], v5 offset:2048
	s_waitcnt lgkmcnt(10)
	v_mfma_f32_32x32x16_bf16 v[50:65], v[170:173], v[138:141], v[50:65]
	v_exp_f32_e32 v126, v126
	v_exp_f32_e32 v127, v127
	v_exp_f32_e32 v128, v128
	v_exp_f32_e32 v129, v129
	ds_read_b128 v[134:137], v5 offset:4096
	s_waitcnt lgkmcnt(9)
	v_mfma_f32_32x32x16_bf16 v[34:49], v[166:169], v[142:145], v[34:49]
	v_exp_f32_e32 v98, v98
	v_exp_f32_e32 v99, v99
	v_exp_f32_e32 v100, v100
	v_exp_f32_e32 v101, v101
	ds_read_b128 v[138:141], v5 offset:6144
	s_waitcnt lgkmcnt(8)
	v_mfma_f32_32x32x16_bf16 v[50:65], v[166:169], v[82:85], v[50:65]
	v_exp_f32_e32 v102, v102
	v_exp_f32_e32 v103, v103
	v_exp_f32_e32 v104, v104
	v_exp_f32_e32 v105, v105
	s_waitcnt lgkmcnt(6)
	v_mfma_f32_32x32x16_bf16 v[34:49], v[162:165], v[86:89], v[34:49]
	v_exp_f32_e32 v106, v106
	v_exp_f32_e32 v107, v107
	v_exp_f32_e32 v108, v108
	v_exp_f32_e32 v109, v109
	s_waitcnt lgkmcnt(4)
	v_mfma_f32_32x32x16_bf16 v[50:65], v[162:165], v[90:93], v[50:65]
	v_exp_f32_e32 v110, v110
	v_exp_f32_e32 v111, v111
	v_exp_f32_e32 v112, v112
	v_exp_f32_e32 v113, v113
	v_add_u32_e32 v3, s25, v3
	ds_read_b64_tr_b16 v[82:83], v3 offset:32768
	ds_read_b64_tr_b16 v[84:85], v3 offset:33280
	v_add_f32_e32 v5, v114, v115
	v_add_f32_e32 v5, v116, v5
	v_add_f32_e32 v5, v117, v5
	v_add_f32_e32 v5, v118, v5
	v_add_f32_e32 v5, v119, v5
	v_cvt_pk_bf16_f32 v178, v114, v115
	v_cvt_pk_bf16_f32 v179, v116, v117
	s_waitcnt lgkmcnt(5)
	v_mfma_f32_32x32x16_bf16 v[66:81], v[94:97], v[182:185], v[66:81]
	ds_read_b64_tr_b16 v[86:87], v3 offset:36864
	ds_read_b64_tr_b16 v[88:89], v3 offset:37376
	v_add_f32_e32 v5, v120, v5
	v_add_f32_e32 v5, v121, v5
	v_add_f32_e32 v5, v122, v5
	v_add_f32_e32 v5, v123, v5
	v_cvt_pk_bf16_f32 v180, v118, v119
	v_cvt_pk_bf16_f32 v181, v120, v121
	ds_read_b64_tr_b16 v[90:91], v3 offset:33792
	ds_read_b64_tr_b16 v[92:93], v3 offset:34304
	v_add_f32_e32 v5, v124, v5
	v_add_f32_e32 v5, v125, v5
	v_add_f32_e32 v5, v126, v5
	v_add_f32_e32 v5, v127, v5
	v_cvt_pk_bf16_f32 v170, v122, v123
	v_cvt_pk_bf16_f32 v171, v124, v125
	s_waitcnt lgkmcnt(8)
	v_mfma_f32_32x32x16_bf16 v[66:81], v[130:133], v[174:177], v[66:81]
	ds_read_b64_tr_b16 v[94:95], v3 offset:37888
	ds_read_b64_tr_b16 v[96:97], v3 offset:38400
	v_add_f32_e32 v5, v128, v5
	v_add_f32_e32 v5, v129, v5
	v_add_f32_e32 v5, v98, v5
	v_add_f32_e32 v5, v99, v5
	v_cvt_pk_bf16_f32 v172, v126, v127
	v_cvt_pk_bf16_f32 v173, v128, v129
	ds_read_b64_tr_b16 v[114:115], v3 offset:34816
	ds_read_b64_tr_b16 v[116:117], v3 offset:35328
	v_add_f32_e32 v5, v100, v5
	v_add_f32_e32 v5, v101, v5
	v_add_f32_e32 v5, v102, v5
	v_add_f32_e32 v5, v103, v5
	v_cvt_pk_bf16_f32 v166, v98, v99
	v_cvt_pk_bf16_f32 v167, v100, v101
	s_waitcnt lgkmcnt(11)
	v_mfma_f32_32x32x16_bf16 v[66:81], v[134:137], v[12:15], v[66:81]
	ds_read_b64_tr_b16 v[98:99], v3 offset:38912
	ds_read_b64_tr_b16 v[100:101], v3 offset:39424
	v_add_f32_e32 v5, v104, v5
	v_add_f32_e32 v5, v105, v5
	v_add_f32_e32 v5, v106, v5
	v_add_f32_e32 v5, v107, v5
	v_cvt_pk_bf16_f32 v168, v102, v103
	v_cvt_pk_bf16_f32 v169, v104, v105
	ds_read_b64_tr_b16 v[102:103], v3 offset:35840
	ds_read_b64_tr_b16 v[104:105], v3 offset:36352
	v_add_f32_e32 v5, v108, v5
	v_add_f32_e32 v5, v109, v5
	v_add_f32_e32 v5, v110, v5
	v_add_f32_e32 v5, v111, v5
	v_cvt_pk_bf16_f32 v162, v106, v107
	v_cvt_pk_bf16_f32 v163, v108, v109
	s_waitcnt lgkmcnt(14)
	v_mfma_f32_32x32x16_bf16 v[66:81], v[138:141], v[8:11], v[66:81]
	ds_read_b64_tr_b16 v[106:107], v3 offset:39936
	ds_read_b64_tr_b16 v[108:109], v3 offset:40448
	v_add_f32_e32 v3, v112, v5
	v_add_f32_e32 v3, v113, v3
	v_add_f32_e32 v3, 0, v3
	v_cvt_pk_bf16_f32 v164, v110, v111
	v_cvt_pk_bf16_f32 v165, v112, v113
	s_nop 0
	v_add_f32_e32 v110, v4, v3
	s_waitcnt lgkmcnt(14)
	v_mfma_f32_32x32x16_bf16 v[34:49], v[178:181], v[82:85], v[34:49]
	s_nop 0
	v_exp_f32_e32 v66, v66
	v_exp_f32_e32 v67, v67
	v_exp_f32_e32 v68, v68
	v_exp_f32_e32 v69, v69
	v_mov_b32_e32 v74, v6
	v_mov_b32_e32 v75, v6
	v_mov_b32_e32 v76, v6
	v_mov_b32_e32 v77, v6
	v_mov_b32_e32 v78, v6
	v_mov_b32_e32 v79, v6
	v_mov_b32_e32 v80, v6
	v_mov_b32_e32 v81, v6
	s_waitcnt lgkmcnt(12)
	v_mfma_f32_32x32x16_bf16 v[50:65], v[178:181], v[86:89], v[50:65]
	v_exp_f32_e32 v70, v70
	v_exp_f32_e32 v71, v71
	v_exp_f32_e32 v72, v72
	v_exp_f32_e32 v73, v73
	s_waitcnt lgkmcnt(10)
	v_mfma_f32_32x32x16_bf16 v[34:49], v[170:173], v[90:93], v[34:49]
	v_exp_f32_e32 v74, v74
	v_exp_f32_e32 v75, v75
	v_exp_f32_e32 v76, v76
	v_exp_f32_e32 v77, v77
	s_waitcnt lgkmcnt(8)
	v_mfma_f32_32x32x16_bf16 v[50:65], v[170:173], v[94:97], v[50:65]
	v_exp_f32_e32 v78, v78
	v_exp_f32_e32 v79, v79
	v_exp_f32_e32 v80, v80
	v_exp_f32_e32 v81, v81
	s_waitcnt lgkmcnt(6)
	v_mfma_f32_32x32x16_bf16 v[34:49], v[166:169], v[114:117], v[34:49]
	v_mov_b32_e32 v16, v6
	v_mov_b32_e32 v17, v6
	v_mov_b32_e32 v3, v2
	v_mov_b32_e32 v4, v2
	v_mov_b32_e32 v5, v2
	v_mov_b32_e32 v7, v6
	v_mov_b32_e32 v8, v6
	v_mov_b32_e32 v9, v6
	v_mov_b32_e32 v10, v6
	v_mov_b32_e32 v11, v6
	v_mov_b32_e32 v12, v6
	v_mov_b32_e32 v13, v6
	v_mov_b32_e32 v14, v6
	v_mov_b32_e32 v15, v6
	v_mov_b64_e32 v[96:97], v[16:17]
	v_mov_b64_e32 v[94:95], v[14:15]
	v_mov_b64_e32 v[92:93], v[12:13]
	v_mov_b64_e32 v[90:91], v[10:11]
	v_mov_b64_e32 v[88:89], v[8:9]
	v_mov_b64_e32 v[86:87], v[6:7]
	v_mov_b64_e32 v[84:85], v[4:5]
	v_mov_b64_e32 v[82:83], v[2:3]
	s_waitcnt lgkmcnt(4)
	v_mfma_f32_32x32x16_bf16 v[50:65], v[166:169], v[98:101], v[50:65]
	v_exp_f32_e32 v86, v86
	v_exp_f32_e32 v87, v87
	v_exp_f32_e32 v88, v88
	v_exp_f32_e32 v89, v89
	s_waitcnt lgkmcnt(2)
	v_mfma_f32_32x32x16_bf16 v[34:49], v[162:165], v[102:105], v[34:49]
	v_exp_f32_e32 v90, v90
	v_exp_f32_e32 v91, v91
	v_exp_f32_e32 v92, v92
	v_exp_f32_e32 v93, v93
	s_waitcnt lgkmcnt(0)
	v_mfma_f32_32x32x16_bf16 v[50:65], v[162:165], v[106:109], v[50:65]
	v_exp_f32_e32 v94, v94
	v_exp_f32_e32 v95, v95
	v_exp_f32_e32 v96, v96
	v_exp_f32_e32 v97, v97
	v_add_f32_e32 v3, v66, v67
	v_add_f32_e32 v3, v68, v3
	v_add_f32_e32 v3, v69, v3
	v_add_f32_e32 v3, v70, v3
	v_add_f32_e32 v3, v71, v3
	v_add_f32_e32 v3, v72, v3
	v_add_f32_e32 v3, v73, v3
	v_add_f32_e32 v3, v74, v3
	v_add_f32_e32 v3, v75, v3
	v_add_f32_e32 v3, v76, v3
	v_add_f32_e32 v3, v77, v3
	v_add_f32_e32 v3, v78, v3
	v_add_f32_e32 v3, v79, v3
	v_add_f32_e32 v3, v80, v3
	v_add_f32_e32 v3, v81, v3
	v_add_f32_e32 v3, v82, v3
	v_add_f32_e32 v3, v83, v3
	v_add_f32_e32 v3, v84, v3
	v_add_f32_e32 v3, v85, v3
	v_add_f32_e32 v3, v86, v3
	v_add_f32_e32 v3, v87, v3
	v_add_f32_e32 v3, v88, v3
	v_add_f32_e32 v3, v89, v3
	v_add_f32_e32 v3, v90, v3
	v_add_f32_e32 v3, v91, v3
	v_add_f32_e32 v3, v92, v3
	v_add_f32_e32 v3, v93, v3
	v_add_f32_e32 v3, v94, v3
	v_add_f32_e32 v3, v95, v3
	s_waitcnt vmcnt(0) lgkmcnt(0)
	s_barrier
	v_add_f32_e32 v3, v96, v3
	v_add_f32_e32 v3, v97, v3
	v_add_f32_e32 v3, v110, v3
	v_cvt_pk_bf16_f32 v8, v66, v67
	v_cvt_pk_bf16_f32 v9, v68, v69
	v_cvt_pk_bf16_f32 v10, v70, v71
	v_cvt_pk_bf16_f32 v11, v72, v73
	v_cvt_pk_bf16_f32 v12, v74, v75
	v_cvt_pk_bf16_f32 v13, v76, v77
	v_cvt_pk_bf16_f32 v14, v78, v79
	v_cvt_pk_bf16_f32 v15, v80, v81
	v_cvt_pk_bf16_f32 v98, v82, v83
	v_cvt_pk_bf16_f32 v99, v84, v85
	v_cvt_pk_bf16_f32 v100, v86, v87
	v_cvt_pk_bf16_f32 v101, v88, v89
	v_cvt_pk_bf16_f32 v102, v90, v91
	v_cvt_pk_bf16_f32 v103, v92, v93
	v_cvt_pk_bf16_f32 v104, v94, v95
	v_cvt_pk_bf16_f32 v105, v96, v97
	v_add3_u32 v4, v218, v217, s24
	ds_read_b64_tr_b16 v[66:67],v4 offset:0
	ds_read_b64_tr_b16 v[68:69],v4 offset:512
	ds_read_b64_tr_b16 v[70:71],v4 offset:1024
	ds_read_b64_tr_b16 v[72:73],v4 offset:1536
	ds_read_b64_tr_b16 v[74:75],v4 offset:2048
	ds_read_b64_tr_b16 v[76:77],v4 offset:2560
	ds_read_b64_tr_b16 v[78:79],v4 offset:3072
	ds_read_b64_tr_b16 v[80:81],v4 offset:3584
	s_waitcnt lgkmcnt(0)
	s_nop 0
	v_mfma_f32_32x32x16_bf16 v[34:49], v[8:11], v[66:69], v[34:49]
	ds_read_b64_tr_b16 v[66:67],v4 offset:4096
	ds_read_b64_tr_b16 v[68:69],v4 offset:4608
	v_mfma_f32_32x32x16_bf16 v[34:49], v[12:15], v[70:73], v[34:49]
	ds_read_b64_tr_b16 v[70:71],v4 offset:5120
	ds_read_b64_tr_b16 v[72:73],v4 offset:5632
	v_mfma_f32_32x32x16_bf16 v[34:49], v[98:101], v[74:77], v[34:49]
	ds_read_b64_tr_b16 v[74:75],v4 offset:6144
	ds_read_b64_tr_b16 v[76:77],v4 offset:6656
	ds_read_b64_tr_b16 v[82:83],v4 offset:7168
	ds_read_b64_tr_b16 v[84:85],v4 offset:7680
	s_waitcnt lgkmcnt(0)
	v_mfma_f32_32x32x16_bf16 v[34:49], v[102:105], v[78:81], v[34:49]
	v_mfma_f32_32x32x16_bf16 v[50:65], v[8:11], v[66:69], v[50:65]
	v_mov_b32_e32 v4, v3
	s_nop 1
	v_permlane32_swap_b32_e32 v3, v4
	v_cmp_gt_u32_e32 vcc, 32, v1
	v_mfma_f32_32x32x16_bf16 v[50:65], v[12:15], v[70:73], v[50:65]
	v_mfma_f32_32x32x16_bf16 v[50:65], v[98:101], v[74:77], v[50:65]
	v_mfma_f32_32x32x16_bf16 v[50:65], v[102:105], v[82:85], v[50:65]
	s_and_saveexec_b64 s[24:25], vcc
	s_cbranch_execz .LBB0_1117
	v_lshl_add_u32 v5, v215, 2, s27
	v_add_f32_e32 v3, v3, v4
	ds_write_b32 v5, v3 offset:128
	s_branch .LBB0_1117
